# v031 + pre2 cache gather: next page-table entry prefetched one page ahead, so the load/convert/store pipeline does not drain at page boundaries
# speedup vs baseline: 1.0006x; 1.0006x over previous
.LBB0_416:
	s_and_b64 vcc, exec, s[0:1]
	s_cbranch_vccz .LBB0_429
	v_mov_b32_e32 v1, v0
	v_readlane_b32 s0, v253, 16
	s_addk_i32 s0, 0x200
	s_waitcnt vmcnt(0)
	v_ashrrev_i32_e32 v2, 6, v1
	v_add_u32_e32 v74, s0, v2
	s_movk_i32 s0, 0x1000
	v_readlane_b32 s1, v253, 17
	v_cmp_gt_i32_e32 vcc, s0, v74
	s_and_saveexec_b64 s[0:1], vcc
	s_cbranch_execz .LBB0_428
	s_load_dwordx2 s[38:39], s[8:9], 0x10
	s_waitcnt lgkmcnt(0)
	s_load_dwordx2 s[24:25], s[8:9], 0x30
	v_readlane_b32 s6, v253, 32
	v_and_b32_e32 v3, 63, v1
	s_add_i32 s28, s6, 0xfffffa00
	v_ashrrev_i32_e32 v75, 31, v74
	v_mov_b32_e32 v77, 0
	v_bfe_u32 v4, v1, 3, 3
	v_lshlrev_b64 v[78:79], 9, v[74:75]
	s_ashr_i32 s29, s28, 31
	v_lshlrev_b32_e32 v76, 4, v3
	v_cmp_eq_u32_e64 s[10:11], 1, v4
	v_cmp_eq_u32_e64 s[12:13], 2, v4
	v_cmp_eq_u32_e64 s[14:15], 3, v4
	v_cmp_eq_u32_e64 s[16:17], 4, v4
	v_cmp_eq_u32_e64 s[18:19], 5, v4
	v_cmp_eq_u32_e64 s[20:21], 6, v4
	v_cmp_eq_u32_e64 s[22:23], 7, v4
	v_lshl_or_b32 v78, v4, 2, v78
	s_lshl_b64 s[30:31], s[28:29], 9
	v_lshl_add_u64 v[4:5], s[38:39], 0, v[76:77]
	s_mov_b64 s[34:35], 0x6800
	s_mov_b32 s29, 0x12000
	v_readlane_b32 s7, v253, 33
	v_lshlrev_b32_e32 v2, 2, v3
	v_and_b32_e32 v1, 7, v1
	v_lshl_add_u64 v[80:81], v[4:5], 0, s[34:35]
	v_mad_i64_i32 v[82:83], s[34:35], v74, s29, 0
	v_cmp_eq_u32_e64 s[6:7], 0, v1
	v_cmp_gt_u32_e64 s[8:9], 8, v3
	v_lshl_or_b32 v82, v3, 3, v82
	s_mul_hi_i32 s35, s28, 0x12000
	s_mul_i32 s34, s28, 0x12000
	s_mov_b64 s[36:37], 0
	s_mov_b32 s29, 0x24000
	v_mov_b64_e32 v[84:85], s[38:39]
	v_lshlrev_b32_e32 v76, 2, v2
	s_mov_b32 s33, 0x1d124000
	s_mov_b32 s46, 0x1d125000
	s_mov_b64 s[38:39], 0x4800
	s_mov_b64 s[40:41], 0x2400
	s_movk_i32 s47, 0xfff
	s_waitcnt lgkmcnt(0)
	v_ashrrev_i32_e32 v75, 31, v74
	v_lshl_add_u64 v[246:247], v[74:75], 2, s[24:25]
	global_load_dword v244, v[246:247], off
	s_waitcnt vmcnt(0)
	s_branch .LBB0_420

.LBB0_420:
	v_ashrrev_i32_e32 v75, 31, v74
	s_waitcnt vmcnt(17) lgkmcnt(0)
	v_mov_b32_e32 v1, v244
	v_add_u32_e32 v246, s28, v74
	v_min_i32_e32 v246, s47, v246
	v_ashrrev_i32_e32 v247, 31, v246
	v_lshl_add_u64 v[246:247], v[246:247], 2, s[24:25]
	global_load_dword v244, v[246:247], off
	v_mov_b64_e32 v[88:89], v[82:83]
	v_mov_b64_e32 v[90:91], v[78:79]
	s_mov_b32 s48, 0
	v_mad_i64_i32 v[2:3], s[42:43], v1, s29, v[84:85]
	v_lshl_add_u64 v[34:35], v[2:3], 0, v[76:77]
	v_add_co_u32_e32 v30, vcc, 0x1000, v34
	global_load_dwordx4 v[2:5], v[34:35], off nt
	global_load_dwordx4 v[6:9], v[34:35], off offset:1024 nt
	global_load_dwordx4 v[10:13], v[34:35], off offset:2048 nt
	global_load_dwordx4 v[14:17], v[34:35], off offset:3072 nt
	v_addc_co_u32_e32 v31, vcc, 0, v35, vcc
	v_add_co_u32_e32 v34, vcc, 0x2000, v34
	global_load_dwordx4 v[18:21], v[30:31], off nt
	global_load_dwordx4 v[22:25], v[30:31], off offset:1024 nt
	global_load_dwordx4 v[26:29], v[30:31], off offset:2048 nt
	s_nop 0
	global_load_dwordx4 v[30:33], v[30:31], off offset:3072 nt
	v_addc_co_u32_e32 v35, vcc, 0, v35, vcc
	global_load_dwordx4 v[34:37], v[34:35], off nt
	v_mad_i64_i32 v[86:87], s[42:43], v1, s29, v[80:81]
	s_branch .LBB0_422
